# speedup vs baseline: 1.0003x; 1.0003x over previous
; __device__ __forceinline__ void dsa_tile(const Params& p, unsigned char* smem, int tile) {
;     ...
;         for (; kb < nkb; kb += 8) {
;             const int kn = (kb + 8 < nkb) ? kb + 8 : kb;
;             const bf16_t* kr = kbase + (size_t)kn * 16 * 64;
;             const u32x4 nx0 = *(const u32x4*)kr, nx1 = *(const u32x4*)(kr + 512);
;             f32x4 s = {0, 0, 0, 0};
;             s = mfma16(x0, chi[0], s); s = mfma16(x1, chi[1], s); s = mfma16(x0, clo[0], s); s = mfma16(x1, clo[1], s);
; #pragma unroll
;             for (int h = 0; h < 16; ++h) {
;                 if ((h & 7) == 0) __builtin_amdgcn_sched_barrier(0);
;                 const float wh = wv[h];
;                 f32x4 d = {0, 0, 0, 0};
;                 d = mfma16(x0, yf[h][0], d); d = mfma16(x1, yf[h][1], d);
; #pragma unroll
;                 for (int j = 0; j < 4; ++j) { float a = __builtin_fmaf(wh, __builtin_fabsf(d[j]), s[j]); asm("" : "+v"(a)); s[j] = a; }
;             }
;             *(f32x4*)(sc + (size_t)fr * SEQ + kb * 16 + fq * 4) = s;
;             x0 = nx0; x1 = nx1;
;         }
.LBB0_289:
	s_add_i32 s11, s12, 8
	s_cmp_gt_i32 s11, s14
	s_cselect_b32 s4, s12, s11
	s_ashr_i32 s5, s4, 31
	s_lshl_b64 s[4:5], s[4:5], 11
	v_lshl_add_u64 v[228:229], v[162:163], 0, s[4:5]
	global_load_dwordx4 v[156:159], v[228:229], off
	global_load_dwordx4 v[152:155], v[228:229], off offset:1024
	s_cmp_eq_u32 s12, s10
	s_cbranch_scc1 .Lidx_nostore
	global_store_dwordx4 v[164:165], v[230:233], off
	s_mov_b64 s[4:5], 0x200
	v_lshl_add_u64 v[164:165], v[164:165], 0, s[4:5]
.Lidx_nostore:
	v_mfma_f32_16x16x32_bf16 v[230:233], v[148:151], v[128:131], 0
	v_mfma_f32_16x16x32_bf16 v[230:233], v[144:147], v[136:139], v[230:233]
	v_mfma_f32_16x16x32_bf16 v[230:233], v[148:151], v[132:135], v[230:233]
	v_mfma_f32_16x16x32_bf16 v[230:233], v[144:147], v[140:143], v[230:233]
	v_mfma_f32_16x16x32_bf16 v[194:197], v[148:151], v[0:3], 0
	v_mfma_f32_16x16x32_bf16 v[198:201], v[148:151], v[8:11], 0
	v_mfma_f32_16x16x32_bf16 v[202:205], v[148:151], v[16:19], 0
	v_mfma_f32_16x16x32_bf16 v[206:209], v[148:151], v[24:27], 0
	v_mfma_f32_16x16x32_bf16 v[194:197], v[144:147], v[4:7], v[194:197]
	v_mfma_f32_16x16x32_bf16 v[198:201], v[144:147], v[12:15], v[198:201]
	v_mfma_f32_16x16x32_bf16 v[202:205], v[144:147], v[20:23], v[202:205]
	v_mfma_f32_16x16x32_bf16 v[206:209], v[144:147], v[28:31], v[206:209]
	v_mfma_f32_16x16x32_bf16 v[210:213], v[148:151], v[32:35], 0
	s_nop 3
	v_fma_f32 v230, v178, |v194|, v230
	v_fma_f32 v231, v178, |v195|, v231
	v_mfma_f32_16x16x32_bf16 v[214:217], v[148:151], v[40:43], 0
	v_fma_f32 v232, v178, |v196|, v232
	v_fma_f32 v233, v178, |v197|, v233
	v_mfma_f32_16x16x32_bf16 v[218:221], v[148:151], v[48:51], 0
	v_fma_f32 v230, v179, |v198|, v230
	v_fma_f32 v231, v179, |v199|, v231
	v_mfma_f32_16x16x32_bf16 v[222:225], v[148:151], v[56:59], 0
	v_fma_f32 v232, v179, |v200|, v232
	v_fma_f32 v233, v179, |v201|, v233
	v_mfma_f32_16x16x32_bf16 v[210:213], v[144:147], v[36:39], v[210:213]
	v_fma_f32 v230, v180, |v202|, v230
	v_fma_f32 v231, v180, |v203|, v231
	v_mfma_f32_16x16x32_bf16 v[214:217], v[144:147], v[44:47], v[214:217]
	v_fma_f32 v232, v180, |v204|, v232
	v_fma_f32 v233, v180, |v205|, v233
	v_mfma_f32_16x16x32_bf16 v[218:221], v[144:147], v[52:55], v[218:221]
	v_fma_f32 v230, v181, |v206|, v230
	v_fma_f32 v231, v181, |v207|, v231
	v_mfma_f32_16x16x32_bf16 v[222:225], v[144:147], v[60:63], v[222:225]
	v_fma_f32 v232, v181, |v208|, v232
	v_fma_f32 v233, v181, |v209|, v233
	v_mfma_f32_16x16x32_bf16 v[194:197], v[148:151], v[64:67], 0
	v_fma_f32 v230, v182, |v210|, v230
	v_fma_f32 v231, v182, |v211|, v231
	v_mfma_f32_16x16x32_bf16 v[198:201], v[148:151], v[72:75], 0
	v_fma_f32 v232, v182, |v212|, v232
	v_fma_f32 v233, v182, |v213|, v233
	v_mfma_f32_16x16x32_bf16 v[202:205], v[148:151], v[80:83], 0
	v_fma_f32 v230, v183, |v214|, v230
	v_fma_f32 v231, v183, |v215|, v231
	v_mfma_f32_16x16x32_bf16 v[206:209], v[148:151], v[88:91], 0
	v_fma_f32 v232, v183, |v216|, v232
	v_fma_f32 v233, v183, |v217|, v233
	v_mfma_f32_16x16x32_bf16 v[194:197], v[144:147], v[68:71], v[194:197]
	v_fma_f32 v230, v184, |v218|, v230
	v_fma_f32 v231, v184, |v219|, v231
	v_mfma_f32_16x16x32_bf16 v[198:201], v[144:147], v[76:79], v[198:201]
	v_fma_f32 v232, v184, |v220|, v232
	v_fma_f32 v233, v184, |v221|, v233
	v_mfma_f32_16x16x32_bf16 v[202:205], v[144:147], v[84:87], v[202:205]
	v_fma_f32 v230, v185, |v222|, v230
	v_fma_f32 v231, v185, |v223|, v231
	v_mfma_f32_16x16x32_bf16 v[206:209], v[144:147], v[92:95], v[206:209]
	v_fma_f32 v232, v185, |v224|, v232
	v_fma_f32 v233, v185, |v225|, v233
	v_mfma_f32_16x16x32_bf16 v[210:213], v[148:151], v[96:99], 0
	v_fma_f32 v230, v186, |v194|, v230
	v_fma_f32 v231, v186, |v195|, v231
	v_mfma_f32_16x16x32_bf16 v[214:217], v[148:151], v[104:107], 0
	v_fma_f32 v232, v186, |v196|, v232
	v_fma_f32 v233, v186, |v197|, v233
	v_mfma_f32_16x16x32_bf16 v[218:221], v[148:151], v[112:115], 0
	v_fma_f32 v230, v187, |v198|, v230
	v_fma_f32 v231, v187, |v199|, v231
	v_mfma_f32_16x16x32_bf16 v[222:225], v[148:151], v[120:123], 0
	v_fma_f32 v232, v187, |v200|, v232
	v_fma_f32 v233, v187, |v201|, v233
	v_mfma_f32_16x16x32_bf16 v[210:213], v[144:147], v[100:103], v[210:213]
	v_fma_f32 v230, v188, |v202|, v230
	v_fma_f32 v231, v188, |v203|, v231
	v_mfma_f32_16x16x32_bf16 v[214:217], v[144:147], v[108:111], v[214:217]
	v_fma_f32 v232, v188, |v204|, v232
	v_fma_f32 v233, v188, |v205|, v233
	v_mfma_f32_16x16x32_bf16 v[218:221], v[144:147], v[116:119], v[218:221]
	v_fma_f32 v230, v189, |v206|, v230
	v_fma_f32 v231, v189, |v207|, v231
	v_mfma_f32_16x16x32_bf16 v[222:225], v[144:147], v[124:127], v[222:225]
	v_fma_f32 v232, v189, |v208|, v232
	v_fma_f32 v233, v189, |v209|, v233
	v_fma_f32 v230, v190, |v210|, v230
	v_fma_f32 v231, v190, |v211|, v231
	v_fma_f32 v232, v190, |v212|, v232
	v_fma_f32 v233, v190, |v213|, v233
	v_fma_f32 v230, v191, |v214|, v230
	v_fma_f32 v231, v191, |v215|, v231
	v_fma_f32 v232, v191, |v216|, v232
	v_fma_f32 v233, v191, |v217|, v233
	v_fma_f32 v230, v192, |v218|, v230
	v_fma_f32 v231, v192, |v219|, v231
	v_fma_f32 v232, v192, |v220|, v232
	v_fma_f32 v233, v192, |v221|, v233
	v_fma_f32 v230, v193, |v222|, v230
	v_fma_f32 v231, v193, |v223|, v231
	v_fma_f32 v232, v193, |v224|, v232
	v_fma_f32 v233, v193, |v225|, v233
	s_cmp_eq_u32 s12, s10
	s_cbranch_scc1 .Lidx_wait0
	s_waitcnt vmcnt(1)
	s_branch .Lidx_waitdone

; __device__ __forceinline__ void dsa_tile(const Params& p, unsigned char* smem, int tile) {
;     ...
;             *(f32x4*)(sc + (size_t)fr * SEQ + kb * 16 + fq * 4) = s;
;             x0 = nx0; x1 = nx1;
;         }
.Lidx_waitdone:
	v_mov_b64_e32 v[148:149], v[156:157]
	v_mov_b64_e32 v[150:151], v[158:159]
	v_mov_b64_e32 v[144:145], v[152:153]
	v_mov_b64_e32 v[146:147], v[154:155]
	s_mov_b32 s12, s11
	s_cmp_le_i32 s11, s14
	s_cbranch_scc1 .LBB0_289
	global_store_dwordx4 v[164:165], v[230:233], off
